# conv GLU and pool staging: the six per-chunk global loads are issued together up front instead of load/wait/process per chunk
# speedup vs baseline: 1.0067x; 1.0025x over previous
; __device__ __forceinline__ int tid_fresh() { int t = threadIdx.x; asm volatile("" : "+v"(t)); return t; }
; __device__ __forceinline__ float sigmoidf_(float x) { return 1.0f / (1.0f + __expf(-x)); }
; __device__ __forceinline__ void conv_item(PP p, unsigned char* shm, int item, int l) {
;     ...
;     const int tid = tid_fresh(), c = tid, row0 = item * 16, b = row0 / SEQ, l0 = row0 % SEQ;
; #pragma unroll
;     for (int i = 0; i < 6; ++i) {
;         const int ci = tid + i * 512, rr = ci >> 6, c8 = ci & 63, ll = l0 - 30 + rr;
;         if (rr < 46) {
;             u32x4 v = (u32x4){0u, 0u, 0u, 0u}, gt = v;
;             if (ll >= 0) { const bf16_t* rp = proj + PJ_UC + (size_t)(b * SEQ + ll) * 1024 + c8 * 8; v = *(const u32x4*)rp; gt = *(const u32x4*)(rp + 512); }
;             float vf[8], gf[8];
;             vf[0] = __uint_as_float(v.x << 16); vf[1] = __uint_as_float(v.x & 0xffff0000u); vf[2] = __uint_as_float(v.y << 16); vf[3] = __uint_as_float(v.y & 0xffff0000u);
;             vf[4] = __uint_as_float(v.z << 16); vf[5] = __uint_as_float(v.z & 0xffff0000u); vf[6] = __uint_as_float(v.w << 16); vf[7] = __uint_as_float(v.w & 0xffff0000u);
;             gf[0] = __uint_as_float(gt.x << 16); gf[1] = __uint_as_float(gt.x & 0xffff0000u); gf[2] = __uint_as_float(gt.y << 16); gf[3] = __uint_as_float(gt.y & 0xffff0000u);
;             gf[4] = __uint_as_float(gt.z << 16); gf[5] = __uint_as_float(gt.z & 0xffff0000u); gf[6] = __uint_as_float(gt.w << 16); gf[7] = __uint_as_float(gt.w & 0xffff0000u);
;             f32x4* d = (f32x4*)(hg + rr * 512 + c8 * 8);
;             d[0] = (f32x4){vf[0] * sigmoidf_(gf[0]), vf[1] * sigmoidf_(gf[1]), vf[2] * sigmoidf_(gf[2]), vf[3] * sigmoidf_(gf[3])};
;             d[1] = (f32x4){vf[4] * sigmoidf_(gf[4]), vf[5] * sigmoidf_(gf[5]), vf[6] * sigmoidf_(gf[6]), vf[7] * sigmoidf_(gf[7])};
;         }
.LBB0_554:
	s_mov_b64 s[28:29], s[0:1]
	s_cmpk_gt_i32 s14, 0x7ff
	s_mov_b64 s[2:3], -1
	s_cbranch_scc0 .LBB0_603
	s_waitcnt lgkmcnt(0)
	s_load_dwordx2 s[34:35], s[28:29], 0x110
	s_cmpk_gt_u32 s14, 0x8ff
	s_cbranch_scc0 .LBB0_581
	v_mov_b32_e32 v10, v222
	s_lshl_b32 s2, s14, 4
	v_and_b32_e32 v4, 63, v10
	s_add_i32 s9, s2, 0xffff7000
	s_and_b32 s2, s2, 0x7f0
	v_lshlrev_b32_e32 v0, 4, v4
	s_sub_i32 s20, s2, 30
	s_waitcnt lgkmcnt(0)
	v_lshl_add_u64 v[2:3], s[34:35], 0, v[0:1]
	s_mov_b64 s[2:3], 0x1ee00000
	v_ashrrev_i32_e32 v14, 6, v10
	s_and_b32 s18, s9, 0x1800
	v_lshl_add_u64 v[12:13], v[2:3], 0, s[2:3]
	v_lshl_add_u32 v11, v4, 5, 0
	v_mov_b32_e32 v130, v10
	v_ashrrev_i32_e32 v130, 6, v130
	v_add_u32_e32 v132, s20, v130
	v_mov_b32_e32 v133, 0
	v_mov_b32_e32 v136, 0
	v_mov_b32_e32 v137, 0
	v_mov_b32_e32 v138, 0
	v_mov_b32_e32 v139, 0
	v_mov_b32_e32 v140, 0
	v_mov_b32_e32 v141, 0
	v_mov_b32_e32 v142, 0
	v_mov_b32_e32 v143, 0
	v_cmp_gt_i32_e32 vcc, 46, v130
	v_cmp_lt_i32_e64 s[2:3], -1, v132
	s_nop 1
	s_and_b64 s[2:3], vcc, s[2:3]
	s_and_saveexec_b64 s[12:13], s[2:3]
	s_cbranch_execz .Lglu_skip_0
	v_add_u32_e32 v132, s18, v132
	v_lshlrev_b64 v[134:135], 11, v[132:133]
	v_lshl_add_u64 v[134:135], v[12:13], 0, v[134:135]
	global_load_dwordx4 v[136:139], v[134:135], off
	global_load_dwordx4 v[140:143], v[134:135], off offset:1024
.Lglu_skip_0:
	s_or_b64 exec, exec, s[12:13]
	v_add_u32_e32 v130, 0x200, v10
	v_ashrrev_i32_e32 v130, 6, v130
	v_add_u32_e32 v132, s20, v130
	v_mov_b32_e32 v133, 0
	v_mov_b32_e32 v144, 0
	v_mov_b32_e32 v145, 0
	v_mov_b32_e32 v146, 0
	v_mov_b32_e32 v147, 0
	v_mov_b32_e32 v148, 0
	v_mov_b32_e32 v149, 0
	v_mov_b32_e32 v150, 0
	v_mov_b32_e32 v151, 0
	v_cmp_gt_i32_e32 vcc, 46, v130
	v_cmp_lt_i32_e64 s[2:3], -1, v132
	s_nop 1
	s_and_b64 s[2:3], vcc, s[2:3]
	s_and_saveexec_b64 s[12:13], s[2:3]
	s_cbranch_execz .Lglu_skip_1
	v_add_u32_e32 v132, s18, v132
	v_lshlrev_b64 v[134:135], 11, v[132:133]
	v_lshl_add_u64 v[134:135], v[12:13], 0, v[134:135]
	global_load_dwordx4 v[144:147], v[134:135], off
	global_load_dwordx4 v[148:151], v[134:135], off offset:1024
.Lglu_skip_1:
	s_or_b64 exec, exec, s[12:13]
	v_add_u32_e32 v130, 0x400, v10
	v_ashrrev_i32_e32 v130, 6, v130
	v_add_u32_e32 v132, s20, v130
	v_mov_b32_e32 v133, 0
	v_mov_b32_e32 v152, 0
	v_mov_b32_e32 v153, 0
	v_mov_b32_e32 v154, 0
	v_mov_b32_e32 v155, 0
	v_mov_b32_e32 v156, 0
	v_mov_b32_e32 v157, 0
	v_mov_b32_e32 v158, 0
	v_mov_b32_e32 v159, 0
	v_cmp_gt_i32_e32 vcc, 46, v130
	v_cmp_lt_i32_e64 s[2:3], -1, v132
	s_nop 1
	s_and_b64 s[2:3], vcc, s[2:3]
	s_and_saveexec_b64 s[12:13], s[2:3]
	s_cbranch_execz .Lglu_skip_2
	v_add_u32_e32 v132, s18, v132
	v_lshlrev_b64 v[134:135], 11, v[132:133]
	v_lshl_add_u64 v[134:135], v[12:13], 0, v[134:135]
	global_load_dwordx4 v[152:155], v[134:135], off
	global_load_dwordx4 v[156:159], v[134:135], off offset:1024
.Lglu_skip_2:
	s_or_b64 exec, exec, s[12:13]
	v_add_u32_e32 v130, 0x600, v10
	v_ashrrev_i32_e32 v130, 6, v130
	v_add_u32_e32 v132, s20, v130
	v_mov_b32_e32 v133, 0
	v_mov_b32_e32 v160, 0
	v_mov_b32_e32 v161, 0
	v_mov_b32_e32 v162, 0
	v_mov_b32_e32 v163, 0
	v_mov_b32_e32 v164, 0
	v_mov_b32_e32 v165, 0
	v_mov_b32_e32 v166, 0
	v_mov_b32_e32 v167, 0
	v_cmp_gt_i32_e32 vcc, 46, v130
	v_cmp_lt_i32_e64 s[2:3], -1, v132
	s_nop 1
	s_and_b64 s[2:3], vcc, s[2:3]
	s_and_saveexec_b64 s[12:13], s[2:3]
	s_cbranch_execz .Lglu_skip_3
	v_add_u32_e32 v132, s18, v132
	v_lshlrev_b64 v[134:135], 11, v[132:133]
	v_lshl_add_u64 v[134:135], v[12:13], 0, v[134:135]
	global_load_dwordx4 v[160:163], v[134:135], off
	global_load_dwordx4 v[164:167], v[134:135], off offset:1024
.Lglu_skip_3:
	s_or_b64 exec, exec, s[12:13]
	v_add_u32_e32 v130, 0x800, v10
	v_ashrrev_i32_e32 v130, 6, v130
	v_add_u32_e32 v132, s20, v130
	v_mov_b32_e32 v133, 0
	v_mov_b32_e32 v168, 0
	v_mov_b32_e32 v169, 0
	v_mov_b32_e32 v170, 0
	v_mov_b32_e32 v171, 0
	v_mov_b32_e32 v172, 0
	v_mov_b32_e32 v173, 0
	v_mov_b32_e32 v174, 0
	v_mov_b32_e32 v175, 0
	v_cmp_gt_i32_e32 vcc, 46, v130
	v_cmp_lt_i32_e64 s[2:3], -1, v132
	s_nop 1
	s_and_b64 s[2:3], vcc, s[2:3]
	s_and_saveexec_b64 s[12:13], s[2:3]
	s_cbranch_execz .Lglu_skip_4
	v_add_u32_e32 v132, s18, v132
	v_lshlrev_b64 v[134:135], 11, v[132:133]
	v_lshl_add_u64 v[134:135], v[12:13], 0, v[134:135]
	global_load_dwordx4 v[168:171], v[134:135], off
	global_load_dwordx4 v[172:175], v[134:135], off offset:1024
.Lglu_skip_4:
	s_or_b64 exec, exec, s[12:13]
	v_add_u32_e32 v130, 0xa00, v10
	v_ashrrev_i32_e32 v130, 6, v130
	v_add_u32_e32 v132, s20, v130
	v_mov_b32_e32 v133, 0
	v_mov_b32_e32 v184, 0
	v_mov_b32_e32 v185, 0
	v_mov_b32_e32 v186, 0
	v_mov_b32_e32 v187, 0
	v_mov_b32_e32 v188, 0
	v_mov_b32_e32 v189, 0
	v_mov_b32_e32 v190, 0
	v_mov_b32_e32 v191, 0
	v_cmp_gt_i32_e32 vcc, 46, v130
	v_cmp_lt_i32_e64 s[2:3], -1, v132
	s_nop 1
	s_and_b64 s[2:3], vcc, s[2:3]
	s_and_saveexec_b64 s[12:13], s[2:3]
	s_cbranch_execz .Lglu_skip_5
	v_add_u32_e32 v132, s18, v132
	v_lshlrev_b64 v[134:135], 11, v[132:133]
	v_lshl_add_u64 v[134:135], v[12:13], 0, v[134:135]
	global_load_dwordx4 v[184:187], v[134:135], off
	global_load_dwordx4 v[188:191], v[134:135], off offset:1024
; __device__ __forceinline__ float sigmoidf_(float x) { return 1.0f / (1.0f + __expf(-x)); }
; __device__ __forceinline__ void conv_item(PP p, unsigned char* shm, int item, int l) {
;     ...
;         if (rr < 46) {
;             u32x4 v = (u32x4){0u, 0u, 0u, 0u}, gt = v;
;             if (ll >= 0) { const bf16_t* rp = proj + PJ_UC + (size_t)(b * SEQ + ll) * 1024 + c8 * 8; v = *(const u32x4*)rp; gt = *(const u32x4*)(rp + 512); }
;             float vf[8], gf[8];
;             vf[0] = __uint_as_float(v.x << 16); vf[1] = __uint_as_float(v.x & 0xffff0000u); vf[2] = __uint_as_float(v.y << 16); vf[3] = __uint_as_float(v.y & 0xffff0000u);
;             vf[4] = __uint_as_float(v.z << 16); vf[5] = __uint_as_float(v.z & 0xffff0000u); vf[6] = __uint_as_float(v.w << 16); vf[7] = __uint_as_float(v.w & 0xffff0000u);
;             gf[0] = __uint_as_float(gt.x << 16); gf[1] = __uint_as_float(gt.x & 0xffff0000u); gf[2] = __uint_as_float(gt.y << 16); gf[3] = __uint_as_float(gt.y & 0xffff0000u);
;             gf[4] = __uint_as_float(gt.z << 16); gf[5] = __uint_as_float(gt.z & 0xffff0000u); gf[6] = __uint_as_float(gt.w << 16); gf[7] = __uint_as_float(gt.w & 0xffff0000u);
;             f32x4* d = (f32x4*)(hg + rr * 512 + c8 * 8);
;             d[0] = (f32x4){vf[0] * sigmoidf_(gf[0]), vf[1] * sigmoidf_(gf[1]), vf[2] * sigmoidf_(gf[2]), vf[3] * sigmoidf_(gf[3])};
;             d[1] = (f32x4){vf[4] * sigmoidf_(gf[4]), vf[5] * sigmoidf_(gf[5]), vf[6] * sigmoidf_(gf[6]), vf[7] * sigmoidf_(gf[7])};
.Lglu_skip_5:
	s_or_b64 exec, exec, s[12:13]
	v_cmp_gt_i32_e32 vcc, 46, v14
	s_and_saveexec_b64 s[12:13], vcc
	s_cbranch_execz .LBB0_560
	s_waitcnt vmcnt(0)
	v_mov_b32_e32 v2, v136
	v_mov_b32_e32 v3, v137
	v_mov_b32_e32 v4, v138
	v_mov_b32_e32 v5, v139
	v_mov_b32_e32 v6, v140
	v_mov_b32_e32 v7, v141
	v_mov_b32_e32 v8, v142
	v_mov_b32_e32 v9, v143
	v_lshlrev_b32_e32 v0, 16, v6
	v_and_b32_e32 v15, 0xffff0000, v6
	v_mul_f32_e32 v0, 0xbfb8aa3b, v0
	v_exp_f32_e32 v6, v0
	v_mul_f32_e32 v0, 0xbfb8aa3b, v15
	v_lshlrev_b32_e32 v16, 16, v7
	v_and_b32_e32 v17, 0xffff0000, v7
	v_exp_f32_e32 v7, v0
	v_lshlrev_b32_e32 v18, 16, v8
	v_and_b32_e32 v19, 0xffff0000, v8
	v_lshlrev_b32_e32 v20, 16, v9
	v_pk_add_f32 v[6:7], v[6:7], 1.0 op_sel_hi:[1,0]
	v_and_b32_e32 v21, 0xffff0000, v9
	v_div_scale_f32 v0, s[2:3], v7, v7, 1.0
	v_lshlrev_b32_e32 v8, 16, v2
	v_and_b32_e32 v9, 0xffff0000, v2
	v_rcp_f32_e32 v2, v0
	v_lshl_add_u32 v14, v14, 11, v11
	v_fma_f32 v15, -v0, v2, 1.0
	v_fmac_f32_e32 v2, v15, v2
	v_div_scale_f32 v15, vcc, 1.0, v7, 1.0
	v_mul_f32_e32 v22, v15, v2
	v_fma_f32 v23, -v0, v22, v15
	v_fmac_f32_e32 v22, v23, v2
	v_fma_f32 v0, -v0, v22, v15
	v_div_fmas_f32 v0, v0, v2, v22
	v_div_fixup_f32 v7, v0, v7, 1.0
	v_div_scale_f32 v0, s[2:3], v6, v6, 1.0
	v_rcp_f32_e32 v2, v0
	s_nop 0
	v_fma_f32 v15, -v0, v2, 1.0
	v_fmac_f32_e32 v2, v15, v2
	v_div_scale_f32 v15, vcc, 1.0, v6, 1.0
	v_mul_f32_e32 v22, v15, v2
	v_fma_f32 v23, -v0, v22, v15
	v_fmac_f32_e32 v22, v23, v2
	v_fma_f32 v0, -v0, v22, v15
	v_div_fmas_f32 v0, v0, v2, v22
	v_div_fixup_f32 v6, v0, v6, 1.0
	v_mul_f32_e32 v0, 0xbfb8aa3b, v16
	v_pk_mul_f32 v[6:7], v[6:7], v[8:9]
	v_exp_f32_e32 v8, v0
	v_mul_f32_e32 v0, 0xbfb8aa3b, v17
	v_exp_f32_e32 v9, v0
	v_lshlrev_b32_e32 v2, 16, v3
	v_and_b32_e32 v3, 0xffff0000, v3
	v_pk_add_f32 v[8:9], v[8:9], 1.0 op_sel_hi:[1,0]
	s_nop 0
	v_div_scale_f32 v0, s[2:3], v9, v9, 1.0
	v_rcp_f32_e32 v15, v0
	s_nop 0
	v_fma_f32 v16, -v0, v15, 1.0
	v_fmac_f32_e32 v15, v16, v15
	v_div_scale_f32 v16, vcc, 1.0, v9, 1.0
	v_mul_f32_e32 v17, v16, v15
	v_fma_f32 v22, -v0, v17, v16
	v_fmac_f32_e32 v17, v22, v15
	v_fma_f32 v0, -v0, v17, v16
	v_div_fmas_f32 v0, v0, v15, v17
	v_div_fixup_f32 v9, v0, v9, 1.0
	v_div_scale_f32 v0, s[2:3], v8, v8, 1.0
	v_rcp_f32_e32 v15, v0
	s_nop 0
	v_fma_f32 v16, -v0, v15, 1.0
	v_fmac_f32_e32 v15, v16, v15
	v_div_scale_f32 v16, vcc, 1.0, v8, 1.0
	v_mul_f32_e32 v17, v16, v15
	v_fma_f32 v22, -v0, v17, v16
	v_fmac_f32_e32 v17, v22, v15
	v_fma_f32 v0, -v0, v17, v16
	v_div_fmas_f32 v0, v0, v15, v17
	v_div_fixup_f32 v8, v0, v8, 1.0
	v_mul_f32_e32 v0, 0xbfb8aa3b, v18
	v_pk_mul_f32 v[8:9], v[8:9], v[2:3]
	v_exp_f32_e32 v2, v0
	v_mul_f32_e32 v0, 0xbfb8aa3b, v19
	v_exp_f32_e32 v3, v0
	ds_write_b128 v14, v[6:9]
	v_lshlrev_b32_e32 v6, 16, v4
	v_and_b32_e32 v7, 0xffff0000, v4
	v_pk_add_f32 v[2:3], v[2:3], 1.0 op_sel_hi:[1,0]
	s_nop 0
	v_div_scale_f32 v0, s[2:3], v3, v3, 1.0
	v_rcp_f32_e32 v4, v0
	s_nop 0
	v_fma_f32 v8, -v0, v4, 1.0
	v_fmac_f32_e32 v4, v8, v4
	v_div_scale_f32 v8, vcc, 1.0, v3, 1.0
	v_mul_f32_e32 v9, v8, v4
	v_fma_f32 v15, -v0, v9, v8
	v_fmac_f32_e32 v9, v15, v4
	v_fma_f32 v0, -v0, v9, v8
	v_div_fmas_f32 v0, v0, v4, v9
	v_div_fixup_f32 v3, v0, v3, 1.0
	v_div_scale_f32 v0, s[2:3], v2, v2, 1.0
	v_rcp_f32_e32 v4, v0
	s_nop 0
	v_fma_f32 v8, -v0, v4, 1.0
	v_fmac_f32_e32 v4, v8, v4
	v_div_scale_f32 v8, vcc, 1.0, v2, 1.0
	v_mul_f32_e32 v9, v8, v4
	v_fma_f32 v15, -v0, v9, v8
	v_fmac_f32_e32 v9, v15, v4
	v_fma_f32 v0, -v0, v9, v8
	v_div_fmas_f32 v0, v0, v4, v9
	v_div_fixup_f32 v2, v0, v2, 1.0
	v_mul_f32_e32 v0, 0xbfb8aa3b, v20
	v_pk_mul_f32 v[2:3], v[2:3], v[6:7]
	v_exp_f32_e32 v6, v0
	v_mul_f32_e32 v0, 0xbfb8aa3b, v21
	v_exp_f32_e32 v7, v0
	v_lshlrev_b32_e32 v4, 16, v5
	v_and_b32_e32 v5, 0xffff0000, v5
	v_pk_add_f32 v[6:7], v[6:7], 1.0 op_sel_hi:[1,0]
	s_nop 0
	v_div_scale_f32 v0, s[2:3], v7, v7, 1.0
	v_rcp_f32_e32 v8, v0
	s_nop 0
	v_fma_f32 v9, -v0, v8, 1.0
	v_fmac_f32_e32 v8, v9, v8
	v_div_scale_f32 v9, vcc, 1.0, v7, 1.0
	v_mul_f32_e32 v15, v9, v8
	v_fma_f32 v16, -v0, v15, v9
	v_fmac_f32_e32 v15, v16, v8
	v_fma_f32 v0, -v0, v15, v9
	v_div_fmas_f32 v0, v0, v8, v15
	v_div_fixup_f32 v7, v0, v7, 1.0
	v_div_scale_f32 v0, s[2:3], v6, v6, 1.0
	v_rcp_f32_e32 v8, v0
	s_nop 0
	v_fma_f32 v9, -v0, v8, 1.0
	v_fmac_f32_e32 v8, v9, v8
	v_div_scale_f32 v9, vcc, 1.0, v6, 1.0
	v_mul_f32_e32 v15, v9, v8
	v_fma_f32 v16, -v0, v15, v9
	v_fmac_f32_e32 v15, v16, v8
	v_fma_f32 v0, -v0, v15, v9
	v_div_fmas_f32 v0, v0, v8, v15
	v_div_fixup_f32 v6, v0, v6, 1.0
	v_pk_mul_f32 v[4:5], v[6:7], v[4:5]
	ds_write_b128 v14, v[2:5] offset:16
; __device__ __forceinline__ float sigmoidf_(float x) { return 1.0f / (1.0f + __expf(-x)); }
; __device__ __forceinline__ void conv_item(PP p, unsigned char* shm, int item, int l) {
;     ...
;     for (int i = 0; i < 6; ++i) {
;         const int ci = tid + i * 512, rr = ci >> 6, c8 = ci & 63, ll = l0 - 30 + rr;
;         if (rr < 46) {
;             u32x4 v = (u32x4){0u, 0u, 0u, 0u}, gt = v;
;             if (ll >= 0) { const bf16_t* rp = proj + PJ_UC + (size_t)(b * SEQ + ll) * 1024 + c8 * 8; v = *(const u32x4*)rp; gt = *(const u32x4*)(rp + 512); }
;             float vf[8], gf[8];
;             vf[0] = __uint_as_float(v.x << 16); vf[1] = __uint_as_float(v.x & 0xffff0000u); vf[2] = __uint_as_float(v.y << 16); vf[3] = __uint_as_float(v.y & 0xffff0000u);
;             vf[4] = __uint_as_float(v.z << 16); vf[5] = __uint_as_float(v.z & 0xffff0000u); vf[6] = __uint_as_float(v.w << 16); vf[7] = __uint_as_float(v.w & 0xffff0000u);
;             gf[0] = __uint_as_float(gt.x << 16); gf[1] = __uint_as_float(gt.x & 0xffff0000u); gf[2] = __uint_as_float(gt.y << 16); gf[3] = __uint_as_float(gt.y & 0xffff0000u);
;             gf[4] = __uint_as_float(gt.z << 16); gf[5] = __uint_as_float(gt.z & 0xffff0000u); gf[6] = __uint_as_float(gt.w << 16); gf[7] = __uint_as_float(gt.w & 0xffff0000u);
;             f32x4* d = (f32x4*)(hg + rr * 512 + c8 * 8);
;             d[0] = (f32x4){vf[0] * sigmoidf_(gf[0]), vf[1] * sigmoidf_(gf[1]), vf[2] * sigmoidf_(gf[2]), vf[3] * sigmoidf_(gf[3])};
;             d[1] = (f32x4){vf[4] * sigmoidf_(gf[4]), vf[5] * sigmoidf_(gf[5]), vf[6] * sigmoidf_(gf[6]), vf[7] * sigmoidf_(gf[7])};
;         }
.LBB0_560:
	s_or_b64 exec, exec, s[12:13]
	v_add_u32_e32 v0, 0x200, v10
	v_ashrrev_i32_e32 v14, 6, v0
	v_cmp_gt_i32_e32 vcc, 46, v14
	s_and_saveexec_b64 s[12:13], vcc
	s_cbranch_execz .LBB0_564
	v_mov_b32_e32 v2, v144
	v_mov_b32_e32 v3, v145
	v_mov_b32_e32 v4, v146
	v_mov_b32_e32 v5, v147
	v_mov_b32_e32 v6, v148
	v_mov_b32_e32 v7, v149
	v_mov_b32_e32 v8, v150
	v_mov_b32_e32 v9, v151
	v_lshlrev_b32_e32 v0, 16, v6
	v_and_b32_e32 v15, 0xffff0000, v6
	v_mul_f32_e32 v0, 0xbfb8aa3b, v0
	v_exp_f32_e32 v6, v0
	v_mul_f32_e32 v0, 0xbfb8aa3b, v15
	v_lshlrev_b32_e32 v16, 16, v7
	v_and_b32_e32 v17, 0xffff0000, v7
	v_exp_f32_e32 v7, v0
	v_lshlrev_b32_e32 v18, 16, v8
	v_and_b32_e32 v19, 0xffff0000, v8
	v_lshlrev_b32_e32 v20, 16, v9
	v_pk_add_f32 v[6:7], v[6:7], 1.0 op_sel_hi:[1,0]
	v_and_b32_e32 v21, 0xffff0000, v9
	v_div_scale_f32 v0, s[2:3], v7, v7, 1.0
	v_lshlrev_b32_e32 v8, 16, v2
	v_and_b32_e32 v9, 0xffff0000, v2
	v_rcp_f32_e32 v2, v0
	v_lshl_add_u32 v14, v14, 11, v11
	v_fma_f32 v15, -v0, v2, 1.0
	v_fmac_f32_e32 v2, v15, v2
	v_div_scale_f32 v15, vcc, 1.0, v7, 1.0
	v_mul_f32_e32 v22, v15, v2
	v_fma_f32 v23, -v0, v22, v15
	v_fmac_f32_e32 v22, v23, v2
	v_fma_f32 v0, -v0, v22, v15
	v_div_fmas_f32 v0, v0, v2, v22
	v_div_fixup_f32 v7, v0, v7, 1.0
	v_div_scale_f32 v0, s[2:3], v6, v6, 1.0
	v_rcp_f32_e32 v2, v0
	s_nop 0
	v_fma_f32 v15, -v0, v2, 1.0
	v_fmac_f32_e32 v2, v15, v2
	v_div_scale_f32 v15, vcc, 1.0, v6, 1.0
	v_mul_f32_e32 v22, v15, v2
	v_fma_f32 v23, -v0, v22, v15
	v_fmac_f32_e32 v22, v23, v2
	v_fma_f32 v0, -v0, v22, v15
	v_div_fmas_f32 v0, v0, v2, v22
	v_div_fixup_f32 v6, v0, v6, 1.0
	v_mul_f32_e32 v0, 0xbfb8aa3b, v16
	v_pk_mul_f32 v[6:7], v[6:7], v[8:9]
	v_exp_f32_e32 v8, v0
	v_mul_f32_e32 v0, 0xbfb8aa3b, v17
	v_exp_f32_e32 v9, v0
	v_lshlrev_b32_e32 v2, 16, v3
	v_and_b32_e32 v3, 0xffff0000, v3
	v_pk_add_f32 v[8:9], v[8:9], 1.0 op_sel_hi:[1,0]
	s_nop 0
	v_div_scale_f32 v0, s[2:3], v9, v9, 1.0
	v_rcp_f32_e32 v15, v0
	s_nop 0
	v_fma_f32 v16, -v0, v15, 1.0
	v_fmac_f32_e32 v15, v16, v15
	v_div_scale_f32 v16, vcc, 1.0, v9, 1.0
	v_mul_f32_e32 v17, v16, v15
	v_fma_f32 v22, -v0, v17, v16
	v_fmac_f32_e32 v17, v22, v15
	v_fma_f32 v0, -v0, v17, v16
	v_div_fmas_f32 v0, v0, v15, v17
	v_div_fixup_f32 v9, v0, v9, 1.0
	v_div_scale_f32 v0, s[2:3], v8, v8, 1.0
	v_rcp_f32_e32 v15, v0
	s_nop 0
	v_fma_f32 v16, -v0, v15, 1.0
	v_fmac_f32_e32 v15, v16, v15
	v_div_scale_f32 v16, vcc, 1.0, v8, 1.0
	v_mul_f32_e32 v17, v16, v15
	v_fma_f32 v22, -v0, v17, v16
	v_fmac_f32_e32 v17, v22, v15
	v_fma_f32 v0, -v0, v17, v16
	v_div_fmas_f32 v0, v0, v15, v17
	v_div_fixup_f32 v8, v0, v8, 1.0
	v_mul_f32_e32 v0, 0xbfb8aa3b, v18
	v_pk_mul_f32 v[8:9], v[8:9], v[2:3]
	v_exp_f32_e32 v2, v0
	v_mul_f32_e32 v0, 0xbfb8aa3b, v19
	v_exp_f32_e32 v3, v0
	ds_write_b128 v14, v[6:9]
	v_lshlrev_b32_e32 v6, 16, v4
	v_and_b32_e32 v7, 0xffff0000, v4
	v_pk_add_f32 v[2:3], v[2:3], 1.0 op_sel_hi:[1,0]
	s_nop 0
	v_div_scale_f32 v0, s[2:3], v3, v3, 1.0
	v_rcp_f32_e32 v4, v0
	s_nop 0
	v_fma_f32 v8, -v0, v4, 1.0
	v_fmac_f32_e32 v4, v8, v4
	v_div_scale_f32 v8, vcc, 1.0, v3, 1.0
	v_mul_f32_e32 v9, v8, v4
	v_fma_f32 v15, -v0, v9, v8
	v_fmac_f32_e32 v9, v15, v4
	v_fma_f32 v0, -v0, v9, v8
	v_div_fmas_f32 v0, v0, v4, v9
	v_div_fixup_f32 v3, v0, v3, 1.0
	v_div_scale_f32 v0, s[2:3], v2, v2, 1.0
	v_rcp_f32_e32 v4, v0
	s_nop 0
	v_fma_f32 v8, -v0, v4, 1.0
	v_fmac_f32_e32 v4, v8, v4
	v_div_scale_f32 v8, vcc, 1.0, v2, 1.0
	v_mul_f32_e32 v9, v8, v4
	v_fma_f32 v15, -v0, v9, v8
	v_fmac_f32_e32 v9, v15, v4
	v_fma_f32 v0, -v0, v9, v8
	v_div_fmas_f32 v0, v0, v4, v9
	v_div_fixup_f32 v2, v0, v2, 1.0
	v_mul_f32_e32 v0, 0xbfb8aa3b, v20
	v_pk_mul_f32 v[2:3], v[2:3], v[6:7]
	v_exp_f32_e32 v6, v0
	v_mul_f32_e32 v0, 0xbfb8aa3b, v21
	v_exp_f32_e32 v7, v0
	v_lshlrev_b32_e32 v4, 16, v5
	v_and_b32_e32 v5, 0xffff0000, v5
	v_pk_add_f32 v[6:7], v[6:7], 1.0 op_sel_hi:[1,0]
	s_nop 0
	v_div_scale_f32 v0, s[2:3], v7, v7, 1.0
	v_rcp_f32_e32 v8, v0
	s_nop 0
	v_fma_f32 v9, -v0, v8, 1.0
	v_fmac_f32_e32 v8, v9, v8
	v_div_scale_f32 v9, vcc, 1.0, v7, 1.0
	v_mul_f32_e32 v15, v9, v8
	v_fma_f32 v16, -v0, v15, v9
	v_fmac_f32_e32 v15, v16, v8
	v_fma_f32 v0, -v0, v15, v9
	v_div_fmas_f32 v0, v0, v8, v15
	v_div_fixup_f32 v7, v0, v7, 1.0
	v_div_scale_f32 v0, s[2:3], v6, v6, 1.0
	v_rcp_f32_e32 v8, v0
	s_nop 0
	v_fma_f32 v9, -v0, v8, 1.0
	v_fmac_f32_e32 v8, v9, v8
	v_div_scale_f32 v9, vcc, 1.0, v6, 1.0
	v_mul_f32_e32 v15, v9, v8
	v_fma_f32 v16, -v0, v15, v9
	v_fmac_f32_e32 v15, v16, v8
	v_fma_f32 v0, -v0, v15, v9
	v_div_fmas_f32 v0, v0, v8, v15
	v_div_fixup_f32 v6, v0, v6, 1.0
	v_pk_mul_f32 v[4:5], v[6:7], v[4:5]
	ds_write_b128 v14, v[2:5] offset:16
; __device__ __forceinline__ float sigmoidf_(float x) { return 1.0f / (1.0f + __expf(-x)); }
; __device__ __forceinline__ void conv_item(PP p, unsigned char* shm, int item, int l) {
;     ...
;     for (int i = 0; i < 6; ++i) {
;         const int ci = tid + i * 512, rr = ci >> 6, c8 = ci & 63, ll = l0 - 30 + rr;
;         if (rr < 46) {
;             u32x4 v = (u32x4){0u, 0u, 0u, 0u}, gt = v;
;             if (ll >= 0) { const bf16_t* rp = proj + PJ_UC + (size_t)(b * SEQ + ll) * 1024 + c8 * 8; v = *(const u32x4*)rp; gt = *(const u32x4*)(rp + 512); }
;             float vf[8], gf[8];
;             vf[0] = __uint_as_float(v.x << 16); vf[1] = __uint_as_float(v.x & 0xffff0000u); vf[2] = __uint_as_float(v.y << 16); vf[3] = __uint_as_float(v.y & 0xffff0000u);
;             vf[4] = __uint_as_float(v.z << 16); vf[5] = __uint_as_float(v.z & 0xffff0000u); vf[6] = __uint_as_float(v.w << 16); vf[7] = __uint_as_float(v.w & 0xffff0000u);
;             gf[0] = __uint_as_float(gt.x << 16); gf[1] = __uint_as_float(gt.x & 0xffff0000u); gf[2] = __uint_as_float(gt.y << 16); gf[3] = __uint_as_float(gt.y & 0xffff0000u);
;             gf[4] = __uint_as_float(gt.z << 16); gf[5] = __uint_as_float(gt.z & 0xffff0000u); gf[6] = __uint_as_float(gt.w << 16); gf[7] = __uint_as_float(gt.w & 0xffff0000u);
;             f32x4* d = (f32x4*)(hg + rr * 512 + c8 * 8);
;             d[0] = (f32x4){vf[0] * sigmoidf_(gf[0]), vf[1] * sigmoidf_(gf[1]), vf[2] * sigmoidf_(gf[2]), vf[3] * sigmoidf_(gf[3])};
;             d[1] = (f32x4){vf[4] * sigmoidf_(gf[4]), vf[5] * sigmoidf_(gf[5]), vf[6] * sigmoidf_(gf[6]), vf[7] * sigmoidf_(gf[7])};
;         }
.LBB0_564:
	s_or_b64 exec, exec, s[12:13]
	v_add_u32_e32 v0, 0x400, v10
	v_ashrrev_i32_e32 v14, 6, v0
	v_cmp_gt_i32_e32 vcc, 46, v14
	s_and_saveexec_b64 s[12:13], vcc
	s_cbranch_execz .LBB0_568
	v_mov_b32_e32 v2, v152
	v_mov_b32_e32 v3, v153
	v_mov_b32_e32 v4, v154
	v_mov_b32_e32 v5, v155
	v_mov_b32_e32 v6, v156
	v_mov_b32_e32 v7, v157
	v_mov_b32_e32 v8, v158
	v_mov_b32_e32 v9, v159
	v_lshlrev_b32_e32 v0, 16, v6
	v_and_b32_e32 v15, 0xffff0000, v6
	v_mul_f32_e32 v0, 0xbfb8aa3b, v0
	v_exp_f32_e32 v6, v0
	v_mul_f32_e32 v0, 0xbfb8aa3b, v15
	v_lshlrev_b32_e32 v16, 16, v7
	v_and_b32_e32 v17, 0xffff0000, v7
	v_exp_f32_e32 v7, v0
	v_lshlrev_b32_e32 v18, 16, v8
	v_and_b32_e32 v19, 0xffff0000, v8
	v_lshlrev_b32_e32 v20, 16, v9
	v_pk_add_f32 v[6:7], v[6:7], 1.0 op_sel_hi:[1,0]
	v_and_b32_e32 v21, 0xffff0000, v9
	v_div_scale_f32 v0, s[2:3], v7, v7, 1.0
	v_lshlrev_b32_e32 v8, 16, v2
	v_and_b32_e32 v9, 0xffff0000, v2
	v_rcp_f32_e32 v2, v0
	v_lshl_add_u32 v14, v14, 11, v11
	v_fma_f32 v15, -v0, v2, 1.0
	v_fmac_f32_e32 v2, v15, v2
	v_div_scale_f32 v15, vcc, 1.0, v7, 1.0
	v_mul_f32_e32 v22, v15, v2
	v_fma_f32 v23, -v0, v22, v15
	v_fmac_f32_e32 v22, v23, v2
	v_fma_f32 v0, -v0, v22, v15
	v_div_fmas_f32 v0, v0, v2, v22
	v_div_fixup_f32 v7, v0, v7, 1.0
	v_div_scale_f32 v0, s[2:3], v6, v6, 1.0
	v_rcp_f32_e32 v2, v0
	s_nop 0
	v_fma_f32 v15, -v0, v2, 1.0
	v_fmac_f32_e32 v2, v15, v2
	v_div_scale_f32 v15, vcc, 1.0, v6, 1.0
	v_mul_f32_e32 v22, v15, v2
	v_fma_f32 v23, -v0, v22, v15
	v_fmac_f32_e32 v22, v23, v2
	v_fma_f32 v0, -v0, v22, v15
	v_div_fmas_f32 v0, v0, v2, v22
	v_div_fixup_f32 v6, v0, v6, 1.0
	v_mul_f32_e32 v0, 0xbfb8aa3b, v16
	v_pk_mul_f32 v[6:7], v[6:7], v[8:9]
	v_exp_f32_e32 v8, v0
	v_mul_f32_e32 v0, 0xbfb8aa3b, v17
	v_exp_f32_e32 v9, v0
	v_lshlrev_b32_e32 v2, 16, v3
	v_and_b32_e32 v3, 0xffff0000, v3
	v_pk_add_f32 v[8:9], v[8:9], 1.0 op_sel_hi:[1,0]
	s_nop 0
	v_div_scale_f32 v0, s[2:3], v9, v9, 1.0
	v_rcp_f32_e32 v15, v0
	s_nop 0
	v_fma_f32 v16, -v0, v15, 1.0
	v_fmac_f32_e32 v15, v16, v15
	v_div_scale_f32 v16, vcc, 1.0, v9, 1.0
	v_mul_f32_e32 v17, v16, v15
	v_fma_f32 v22, -v0, v17, v16
	v_fmac_f32_e32 v17, v22, v15
	v_fma_f32 v0, -v0, v17, v16
	v_div_fmas_f32 v0, v0, v15, v17
	v_div_fixup_f32 v9, v0, v9, 1.0
	v_div_scale_f32 v0, s[2:3], v8, v8, 1.0
	v_rcp_f32_e32 v15, v0
	s_nop 0
	v_fma_f32 v16, -v0, v15, 1.0
	v_fmac_f32_e32 v15, v16, v15
	v_div_scale_f32 v16, vcc, 1.0, v8, 1.0
	v_mul_f32_e32 v17, v16, v15
	v_fma_f32 v22, -v0, v17, v16
	v_fmac_f32_e32 v17, v22, v15
	v_fma_f32 v0, -v0, v17, v16
	v_div_fmas_f32 v0, v0, v15, v17
	v_div_fixup_f32 v8, v0, v8, 1.0
	v_mul_f32_e32 v0, 0xbfb8aa3b, v18
	v_pk_mul_f32 v[8:9], v[8:9], v[2:3]
	v_exp_f32_e32 v2, v0
	v_mul_f32_e32 v0, 0xbfb8aa3b, v19
	v_exp_f32_e32 v3, v0
	ds_write_b128 v14, v[6:9]
	v_lshlrev_b32_e32 v6, 16, v4
	v_and_b32_e32 v7, 0xffff0000, v4
	v_pk_add_f32 v[2:3], v[2:3], 1.0 op_sel_hi:[1,0]
	s_nop 0
	v_div_scale_f32 v0, s[2:3], v3, v3, 1.0
	v_rcp_f32_e32 v4, v0
	s_nop 0
	v_fma_f32 v8, -v0, v4, 1.0
	v_fmac_f32_e32 v4, v8, v4
	v_div_scale_f32 v8, vcc, 1.0, v3, 1.0
	v_mul_f32_e32 v9, v8, v4
	v_fma_f32 v15, -v0, v9, v8
	v_fmac_f32_e32 v9, v15, v4
	v_fma_f32 v0, -v0, v9, v8
	v_div_fmas_f32 v0, v0, v4, v9
	v_div_fixup_f32 v3, v0, v3, 1.0
	v_div_scale_f32 v0, s[2:3], v2, v2, 1.0
	v_rcp_f32_e32 v4, v0
	s_nop 0
	v_fma_f32 v8, -v0, v4, 1.0
	v_fmac_f32_e32 v4, v8, v4
	v_div_scale_f32 v8, vcc, 1.0, v2, 1.0
	v_mul_f32_e32 v9, v8, v4
	v_fma_f32 v15, -v0, v9, v8
	v_fmac_f32_e32 v9, v15, v4
	v_fma_f32 v0, -v0, v9, v8
	v_div_fmas_f32 v0, v0, v4, v9
	v_div_fixup_f32 v2, v0, v2, 1.0
	v_mul_f32_e32 v0, 0xbfb8aa3b, v20
	v_pk_mul_f32 v[2:3], v[2:3], v[6:7]
	v_exp_f32_e32 v6, v0
	v_mul_f32_e32 v0, 0xbfb8aa3b, v21
	v_exp_f32_e32 v7, v0
	v_lshlrev_b32_e32 v4, 16, v5
	v_and_b32_e32 v5, 0xffff0000, v5
	v_pk_add_f32 v[6:7], v[6:7], 1.0 op_sel_hi:[1,0]
	s_nop 0
	v_div_scale_f32 v0, s[2:3], v7, v7, 1.0
	v_rcp_f32_e32 v8, v0
	s_nop 0
	v_fma_f32 v9, -v0, v8, 1.0
	v_fmac_f32_e32 v8, v9, v8
	v_div_scale_f32 v9, vcc, 1.0, v7, 1.0
	v_mul_f32_e32 v15, v9, v8
	v_fma_f32 v16, -v0, v15, v9
	v_fmac_f32_e32 v15, v16, v8
	v_fma_f32 v0, -v0, v15, v9
	v_div_fmas_f32 v0, v0, v8, v15
	v_div_fixup_f32 v7, v0, v7, 1.0
	v_div_scale_f32 v0, s[2:3], v6, v6, 1.0
	v_rcp_f32_e32 v8, v0
	s_nop 0
	v_fma_f32 v9, -v0, v8, 1.0
	v_fmac_f32_e32 v8, v9, v8
	v_div_scale_f32 v9, vcc, 1.0, v6, 1.0
	v_mul_f32_e32 v15, v9, v8
	v_fma_f32 v16, -v0, v15, v9
	v_fmac_f32_e32 v15, v16, v8
	v_fma_f32 v0, -v0, v15, v9
	v_div_fmas_f32 v0, v0, v8, v15
	v_div_fixup_f32 v6, v0, v6, 1.0
	v_pk_mul_f32 v[4:5], v[6:7], v[4:5]
	ds_write_b128 v14, v[2:5] offset:16
; __device__ __forceinline__ float sigmoidf_(float x) { return 1.0f / (1.0f + __expf(-x)); }
; __device__ __forceinline__ void conv_item(PP p, unsigned char* shm, int item, int l) {
;     ...
;     for (int i = 0; i < 6; ++i) {
;         const int ci = tid + i * 512, rr = ci >> 6, c8 = ci & 63, ll = l0 - 30 + rr;
;         if (rr < 46) {
;             u32x4 v = (u32x4){0u, 0u, 0u, 0u}, gt = v;
;             if (ll >= 0) { const bf16_t* rp = proj + PJ_UC + (size_t)(b * SEQ + ll) * 1024 + c8 * 8; v = *(const u32x4*)rp; gt = *(const u32x4*)(rp + 512); }
;             float vf[8], gf[8];
;             vf[0] = __uint_as_float(v.x << 16); vf[1] = __uint_as_float(v.x & 0xffff0000u); vf[2] = __uint_as_float(v.y << 16); vf[3] = __uint_as_float(v.y & 0xffff0000u);
;             vf[4] = __uint_as_float(v.z << 16); vf[5] = __uint_as_float(v.z & 0xffff0000u); vf[6] = __uint_as_float(v.w << 16); vf[7] = __uint_as_float(v.w & 0xffff0000u);
;             gf[0] = __uint_as_float(gt.x << 16); gf[1] = __uint_as_float(gt.x & 0xffff0000u); gf[2] = __uint_as_float(gt.y << 16); gf[3] = __uint_as_float(gt.y & 0xffff0000u);
;             gf[4] = __uint_as_float(gt.z << 16); gf[5] = __uint_as_float(gt.z & 0xffff0000u); gf[6] = __uint_as_float(gt.w << 16); gf[7] = __uint_as_float(gt.w & 0xffff0000u);
;             f32x4* d = (f32x4*)(hg + rr * 512 + c8 * 8);
;             d[0] = (f32x4){vf[0] * sigmoidf_(gf[0]), vf[1] * sigmoidf_(gf[1]), vf[2] * sigmoidf_(gf[2]), vf[3] * sigmoidf_(gf[3])};
;             d[1] = (f32x4){vf[4] * sigmoidf_(gf[4]), vf[5] * sigmoidf_(gf[5]), vf[6] * sigmoidf_(gf[6]), vf[7] * sigmoidf_(gf[7])};
;         }
.LBB0_568:
	s_or_b64 exec, exec, s[12:13]
	v_add_u32_e32 v0, 0x600, v10
	v_ashrrev_i32_e32 v14, 6, v0
	v_cmp_gt_i32_e32 vcc, 46, v14
	s_and_saveexec_b64 s[12:13], vcc
	s_cbranch_execz .LBB0_572
	v_mov_b32_e32 v2, v160
	v_mov_b32_e32 v3, v161
	v_mov_b32_e32 v4, v162
	v_mov_b32_e32 v5, v163
	v_mov_b32_e32 v6, v164
	v_mov_b32_e32 v7, v165
	v_mov_b32_e32 v8, v166
	v_mov_b32_e32 v9, v167
	v_lshlrev_b32_e32 v0, 16, v6
	v_and_b32_e32 v15, 0xffff0000, v6
	v_mul_f32_e32 v0, 0xbfb8aa3b, v0
	v_exp_f32_e32 v6, v0
	v_mul_f32_e32 v0, 0xbfb8aa3b, v15
	v_lshlrev_b32_e32 v16, 16, v7
	v_and_b32_e32 v17, 0xffff0000, v7
	v_exp_f32_e32 v7, v0
	v_lshlrev_b32_e32 v18, 16, v8
	v_and_b32_e32 v19, 0xffff0000, v8
	v_lshlrev_b32_e32 v20, 16, v9
	v_pk_add_f32 v[6:7], v[6:7], 1.0 op_sel_hi:[1,0]
	v_and_b32_e32 v21, 0xffff0000, v9
	v_div_scale_f32 v0, s[2:3], v7, v7, 1.0
	v_lshlrev_b32_e32 v8, 16, v2
	v_and_b32_e32 v9, 0xffff0000, v2
	v_rcp_f32_e32 v2, v0
	v_lshl_add_u32 v14, v14, 11, v11
	v_fma_f32 v15, -v0, v2, 1.0
	v_fmac_f32_e32 v2, v15, v2
	v_div_scale_f32 v15, vcc, 1.0, v7, 1.0
	v_mul_f32_e32 v22, v15, v2
	v_fma_f32 v23, -v0, v22, v15
	v_fmac_f32_e32 v22, v23, v2
	v_fma_f32 v0, -v0, v22, v15
	v_div_fmas_f32 v0, v0, v2, v22
	v_div_fixup_f32 v7, v0, v7, 1.0
	v_div_scale_f32 v0, s[2:3], v6, v6, 1.0
	v_rcp_f32_e32 v2, v0
	s_nop 0
	v_fma_f32 v15, -v0, v2, 1.0
	v_fmac_f32_e32 v2, v15, v2
	v_div_scale_f32 v15, vcc, 1.0, v6, 1.0
	v_mul_f32_e32 v22, v15, v2
	v_fma_f32 v23, -v0, v22, v15
	v_fmac_f32_e32 v22, v23, v2
	v_fma_f32 v0, -v0, v22, v15
	v_div_fmas_f32 v0, v0, v2, v22
	v_div_fixup_f32 v6, v0, v6, 1.0
	v_mul_f32_e32 v0, 0xbfb8aa3b, v16
	v_pk_mul_f32 v[6:7], v[6:7], v[8:9]
	v_exp_f32_e32 v8, v0
	v_mul_f32_e32 v0, 0xbfb8aa3b, v17
	v_exp_f32_e32 v9, v0
	v_lshlrev_b32_e32 v2, 16, v3
	v_and_b32_e32 v3, 0xffff0000, v3
	v_pk_add_f32 v[8:9], v[8:9], 1.0 op_sel_hi:[1,0]
	s_nop 0
	v_div_scale_f32 v0, s[2:3], v9, v9, 1.0
	v_rcp_f32_e32 v15, v0
	s_nop 0
	v_fma_f32 v16, -v0, v15, 1.0
	v_fmac_f32_e32 v15, v16, v15
	v_div_scale_f32 v16, vcc, 1.0, v9, 1.0
	v_mul_f32_e32 v17, v16, v15
	v_fma_f32 v22, -v0, v17, v16
	v_fmac_f32_e32 v17, v22, v15
	v_fma_f32 v0, -v0, v17, v16
	v_div_fmas_f32 v0, v0, v15, v17
	v_div_fixup_f32 v9, v0, v9, 1.0
	v_div_scale_f32 v0, s[2:3], v8, v8, 1.0
	v_rcp_f32_e32 v15, v0
	s_nop 0
	v_fma_f32 v16, -v0, v15, 1.0
	v_fmac_f32_e32 v15, v16, v15
	v_div_scale_f32 v16, vcc, 1.0, v8, 1.0
	v_mul_f32_e32 v17, v16, v15
	v_fma_f32 v22, -v0, v17, v16
	v_fmac_f32_e32 v17, v22, v15
	v_fma_f32 v0, -v0, v17, v16
	v_div_fmas_f32 v0, v0, v15, v17
	v_div_fixup_f32 v8, v0, v8, 1.0
	v_mul_f32_e32 v0, 0xbfb8aa3b, v18
	v_pk_mul_f32 v[8:9], v[8:9], v[2:3]
	v_exp_f32_e32 v2, v0
	v_mul_f32_e32 v0, 0xbfb8aa3b, v19
	v_exp_f32_e32 v3, v0
	ds_write_b128 v14, v[6:9]
	v_lshlrev_b32_e32 v6, 16, v4
	v_and_b32_e32 v7, 0xffff0000, v4
	v_pk_add_f32 v[2:3], v[2:3], 1.0 op_sel_hi:[1,0]
	s_nop 0
	v_div_scale_f32 v0, s[2:3], v3, v3, 1.0
	v_rcp_f32_e32 v4, v0
	s_nop 0
	v_fma_f32 v8, -v0, v4, 1.0
	v_fmac_f32_e32 v4, v8, v4
	v_div_scale_f32 v8, vcc, 1.0, v3, 1.0
	v_mul_f32_e32 v9, v8, v4
	v_fma_f32 v15, -v0, v9, v8
	v_fmac_f32_e32 v9, v15, v4
	v_fma_f32 v0, -v0, v9, v8
	v_div_fmas_f32 v0, v0, v4, v9
	v_div_fixup_f32 v3, v0, v3, 1.0
	v_div_scale_f32 v0, s[2:3], v2, v2, 1.0
	v_rcp_f32_e32 v4, v0
	s_nop 0
	v_fma_f32 v8, -v0, v4, 1.0
	v_fmac_f32_e32 v4, v8, v4
	v_div_scale_f32 v8, vcc, 1.0, v2, 1.0
	v_mul_f32_e32 v9, v8, v4
	v_fma_f32 v15, -v0, v9, v8
	v_fmac_f32_e32 v9, v15, v4
	v_fma_f32 v0, -v0, v9, v8
	v_div_fmas_f32 v0, v0, v4, v9
	v_div_fixup_f32 v2, v0, v2, 1.0
	v_mul_f32_e32 v0, 0xbfb8aa3b, v20
	v_pk_mul_f32 v[2:3], v[2:3], v[6:7]
	v_exp_f32_e32 v6, v0
	v_mul_f32_e32 v0, 0xbfb8aa3b, v21
	v_exp_f32_e32 v7, v0
	v_lshlrev_b32_e32 v4, 16, v5
	v_and_b32_e32 v5, 0xffff0000, v5
	v_pk_add_f32 v[6:7], v[6:7], 1.0 op_sel_hi:[1,0]
	s_nop 0
	v_div_scale_f32 v0, s[2:3], v7, v7, 1.0
	v_rcp_f32_e32 v8, v0
	s_nop 0
	v_fma_f32 v9, -v0, v8, 1.0
	v_fmac_f32_e32 v8, v9, v8
	v_div_scale_f32 v9, vcc, 1.0, v7, 1.0
	v_mul_f32_e32 v15, v9, v8
	v_fma_f32 v16, -v0, v15, v9
	v_fmac_f32_e32 v15, v16, v8
	v_fma_f32 v0, -v0, v15, v9
	v_div_fmas_f32 v0, v0, v8, v15
	v_div_fixup_f32 v7, v0, v7, 1.0
	v_div_scale_f32 v0, s[2:3], v6, v6, 1.0
	v_rcp_f32_e32 v8, v0
	s_nop 0
	v_fma_f32 v9, -v0, v8, 1.0
	v_fmac_f32_e32 v8, v9, v8
	v_div_scale_f32 v9, vcc, 1.0, v6, 1.0
	v_mul_f32_e32 v15, v9, v8
	v_fma_f32 v16, -v0, v15, v9
	v_fmac_f32_e32 v15, v16, v8
	v_fma_f32 v0, -v0, v15, v9
	v_div_fmas_f32 v0, v0, v8, v15
	v_div_fixup_f32 v6, v0, v6, 1.0
	v_pk_mul_f32 v[4:5], v[6:7], v[4:5]
	ds_write_b128 v14, v[2:5] offset:16
; __device__ __forceinline__ float sigmoidf_(float x) { return 1.0f / (1.0f + __expf(-x)); }
; __device__ __forceinline__ void conv_item(PP p, unsigned char* shm, int item, int l) {
;     ...
;     for (int i = 0; i < 6; ++i) {
;         const int ci = tid + i * 512, rr = ci >> 6, c8 = ci & 63, ll = l0 - 30 + rr;
;         if (rr < 46) {
;             u32x4 v = (u32x4){0u, 0u, 0u, 0u}, gt = v;
;             if (ll >= 0) { const bf16_t* rp = proj + PJ_UC + (size_t)(b * SEQ + ll) * 1024 + c8 * 8; v = *(const u32x4*)rp; gt = *(const u32x4*)(rp + 512); }
;             float vf[8], gf[8];
;             vf[0] = __uint_as_float(v.x << 16); vf[1] = __uint_as_float(v.x & 0xffff0000u); vf[2] = __uint_as_float(v.y << 16); vf[3] = __uint_as_float(v.y & 0xffff0000u);
;             vf[4] = __uint_as_float(v.z << 16); vf[5] = __uint_as_float(v.z & 0xffff0000u); vf[6] = __uint_as_float(v.w << 16); vf[7] = __uint_as_float(v.w & 0xffff0000u);
;             gf[0] = __uint_as_float(gt.x << 16); gf[1] = __uint_as_float(gt.x & 0xffff0000u); gf[2] = __uint_as_float(gt.y << 16); gf[3] = __uint_as_float(gt.y & 0xffff0000u);
;             gf[4] = __uint_as_float(gt.z << 16); gf[5] = __uint_as_float(gt.z & 0xffff0000u); gf[6] = __uint_as_float(gt.w << 16); gf[7] = __uint_as_float(gt.w & 0xffff0000u);
;             f32x4* d = (f32x4*)(hg + rr * 512 + c8 * 8);
;             d[0] = (f32x4){vf[0] * sigmoidf_(gf[0]), vf[1] * sigmoidf_(gf[1]), vf[2] * sigmoidf_(gf[2]), vf[3] * sigmoidf_(gf[3])};
;             d[1] = (f32x4){vf[4] * sigmoidf_(gf[4]), vf[5] * sigmoidf_(gf[5]), vf[6] * sigmoidf_(gf[6]), vf[7] * sigmoidf_(gf[7])};
;         }
.LBB0_572:
	s_or_b64 exec, exec, s[12:13]
	v_add_u32_e32 v0, 0x800, v10
	v_ashrrev_i32_e32 v14, 6, v0
	v_cmp_gt_i32_e32 vcc, 46, v14
	s_and_saveexec_b64 s[12:13], vcc
	s_cbranch_execz .LBB0_576
	v_mov_b32_e32 v2, v168
	v_mov_b32_e32 v3, v169
	v_mov_b32_e32 v4, v170
	v_mov_b32_e32 v5, v171
	v_mov_b32_e32 v6, v172
	v_mov_b32_e32 v7, v173
	v_mov_b32_e32 v8, v174
	v_mov_b32_e32 v9, v175
	v_lshlrev_b32_e32 v0, 16, v6
	v_and_b32_e32 v15, 0xffff0000, v6
	v_mul_f32_e32 v0, 0xbfb8aa3b, v0
	v_exp_f32_e32 v6, v0
	v_mul_f32_e32 v0, 0xbfb8aa3b, v15
	v_lshlrev_b32_e32 v16, 16, v7
	v_and_b32_e32 v17, 0xffff0000, v7
	v_exp_f32_e32 v7, v0
	v_lshlrev_b32_e32 v18, 16, v8
	v_and_b32_e32 v19, 0xffff0000, v8
	v_lshlrev_b32_e32 v20, 16, v9
	v_pk_add_f32 v[6:7], v[6:7], 1.0 op_sel_hi:[1,0]
	v_and_b32_e32 v21, 0xffff0000, v9
	v_div_scale_f32 v0, s[2:3], v7, v7, 1.0
	v_lshlrev_b32_e32 v8, 16, v2
	v_and_b32_e32 v9, 0xffff0000, v2
	v_rcp_f32_e32 v2, v0
	v_lshl_add_u32 v14, v14, 11, v11
	v_fma_f32 v15, -v0, v2, 1.0
	v_fmac_f32_e32 v2, v15, v2
	v_div_scale_f32 v15, vcc, 1.0, v7, 1.0
	v_mul_f32_e32 v22, v15, v2
	v_fma_f32 v23, -v0, v22, v15
	v_fmac_f32_e32 v22, v23, v2
	v_fma_f32 v0, -v0, v22, v15
	v_div_fmas_f32 v0, v0, v2, v22
	v_div_fixup_f32 v7, v0, v7, 1.0
	v_div_scale_f32 v0, s[2:3], v6, v6, 1.0
	v_rcp_f32_e32 v2, v0
	s_nop 0
	v_fma_f32 v15, -v0, v2, 1.0
	v_fmac_f32_e32 v2, v15, v2
	v_div_scale_f32 v15, vcc, 1.0, v6, 1.0
	v_mul_f32_e32 v22, v15, v2
	v_fma_f32 v23, -v0, v22, v15
	v_fmac_f32_e32 v22, v23, v2
	v_fma_f32 v0, -v0, v22, v15
	v_div_fmas_f32 v0, v0, v2, v22
	v_div_fixup_f32 v6, v0, v6, 1.0
	v_mul_f32_e32 v0, 0xbfb8aa3b, v16
	v_pk_mul_f32 v[6:7], v[6:7], v[8:9]
	v_exp_f32_e32 v8, v0
	v_mul_f32_e32 v0, 0xbfb8aa3b, v17
	v_exp_f32_e32 v9, v0
	v_lshlrev_b32_e32 v2, 16, v3
	v_and_b32_e32 v3, 0xffff0000, v3
	v_pk_add_f32 v[8:9], v[8:9], 1.0 op_sel_hi:[1,0]
	s_nop 0
	v_div_scale_f32 v0, s[2:3], v9, v9, 1.0
	v_rcp_f32_e32 v15, v0
	s_nop 0
	v_fma_f32 v16, -v0, v15, 1.0
	v_fmac_f32_e32 v15, v16, v15
	v_div_scale_f32 v16, vcc, 1.0, v9, 1.0
	v_mul_f32_e32 v17, v16, v15
	v_fma_f32 v22, -v0, v17, v16
	v_fmac_f32_e32 v17, v22, v15
	v_fma_f32 v0, -v0, v17, v16
	v_div_fmas_f32 v0, v0, v15, v17
	v_div_fixup_f32 v9, v0, v9, 1.0
	v_div_scale_f32 v0, s[2:3], v8, v8, 1.0
	v_rcp_f32_e32 v15, v0
	s_nop 0
	v_fma_f32 v16, -v0, v15, 1.0
	v_fmac_f32_e32 v15, v16, v15
	v_div_scale_f32 v16, vcc, 1.0, v8, 1.0
	v_mul_f32_e32 v17, v16, v15
	v_fma_f32 v22, -v0, v17, v16
	v_fmac_f32_e32 v17, v22, v15
	v_fma_f32 v0, -v0, v17, v16
	v_div_fmas_f32 v0, v0, v15, v17
	v_div_fixup_f32 v8, v0, v8, 1.0
	v_mul_f32_e32 v0, 0xbfb8aa3b, v18
	v_pk_mul_f32 v[8:9], v[8:9], v[2:3]
	v_exp_f32_e32 v2, v0
	v_mul_f32_e32 v0, 0xbfb8aa3b, v19
	v_exp_f32_e32 v3, v0
	ds_write_b128 v14, v[6:9]
	v_lshlrev_b32_e32 v6, 16, v4
	v_and_b32_e32 v7, 0xffff0000, v4
	v_pk_add_f32 v[2:3], v[2:3], 1.0 op_sel_hi:[1,0]
	s_nop 0
	v_div_scale_f32 v0, s[2:3], v3, v3, 1.0
	v_rcp_f32_e32 v4, v0
	s_nop 0
	v_fma_f32 v8, -v0, v4, 1.0
	v_fmac_f32_e32 v4, v8, v4
	v_div_scale_f32 v8, vcc, 1.0, v3, 1.0
	v_mul_f32_e32 v9, v8, v4
	v_fma_f32 v15, -v0, v9, v8
	v_fmac_f32_e32 v9, v15, v4
	v_fma_f32 v0, -v0, v9, v8
	v_div_fmas_f32 v0, v0, v4, v9
	v_div_fixup_f32 v3, v0, v3, 1.0
	v_div_scale_f32 v0, s[2:3], v2, v2, 1.0
	v_rcp_f32_e32 v4, v0
	s_nop 0
	v_fma_f32 v8, -v0, v4, 1.0
	v_fmac_f32_e32 v4, v8, v4
	v_div_scale_f32 v8, vcc, 1.0, v2, 1.0
	v_mul_f32_e32 v9, v8, v4
	v_fma_f32 v15, -v0, v9, v8
	v_fmac_f32_e32 v9, v15, v4
	v_fma_f32 v0, -v0, v9, v8
	v_div_fmas_f32 v0, v0, v4, v9
	v_div_fixup_f32 v2, v0, v2, 1.0
	v_mul_f32_e32 v0, 0xbfb8aa3b, v20
	v_pk_mul_f32 v[2:3], v[2:3], v[6:7]
	v_exp_f32_e32 v6, v0
	v_mul_f32_e32 v0, 0xbfb8aa3b, v21
	v_exp_f32_e32 v7, v0
	v_lshlrev_b32_e32 v4, 16, v5
	v_and_b32_e32 v5, 0xffff0000, v5
	v_pk_add_f32 v[6:7], v[6:7], 1.0 op_sel_hi:[1,0]
	s_nop 0
	v_div_scale_f32 v0, s[2:3], v7, v7, 1.0
	v_rcp_f32_e32 v8, v0
	s_nop 0
	v_fma_f32 v9, -v0, v8, 1.0
	v_fmac_f32_e32 v8, v9, v8
	v_div_scale_f32 v9, vcc, 1.0, v7, 1.0
	v_mul_f32_e32 v15, v9, v8
	v_fma_f32 v16, -v0, v15, v9
	v_fmac_f32_e32 v15, v16, v8
	v_fma_f32 v0, -v0, v15, v9
	v_div_fmas_f32 v0, v0, v8, v15
	v_div_fixup_f32 v7, v0, v7, 1.0
	v_div_scale_f32 v0, s[2:3], v6, v6, 1.0
	v_rcp_f32_e32 v8, v0
	s_nop 0
	v_fma_f32 v9, -v0, v8, 1.0
	v_fmac_f32_e32 v8, v9, v8
	v_div_scale_f32 v9, vcc, 1.0, v6, 1.0
	v_mul_f32_e32 v15, v9, v8
	v_fma_f32 v16, -v0, v15, v9
	v_fmac_f32_e32 v15, v16, v8
	v_fma_f32 v0, -v0, v15, v9
	v_div_fmas_f32 v0, v0, v8, v15
	v_div_fixup_f32 v6, v0, v6, 1.0
	v_pk_mul_f32 v[4:5], v[6:7], v[4:5]
	ds_write_b128 v14, v[2:5] offset:16
; __device__ __forceinline__ float sigmoidf_(float x) { return 1.0f / (1.0f + __expf(-x)); }
; __device__ __forceinline__ void conv_item(PP p, unsigned char* shm, int item, int l) {
;     ...
;     for (int i = 0; i < 6; ++i) {
;         const int ci = tid + i * 512, rr = ci >> 6, c8 = ci & 63, ll = l0 - 30 + rr;
;         if (rr < 46) {
;             u32x4 v = (u32x4){0u, 0u, 0u, 0u}, gt = v;
;             if (ll >= 0) { const bf16_t* rp = proj + PJ_UC + (size_t)(b * SEQ + ll) * 1024 + c8 * 8; v = *(const u32x4*)rp; gt = *(const u32x4*)(rp + 512); }
;             float vf[8], gf[8];
;             vf[0] = __uint_as_float(v.x << 16); vf[1] = __uint_as_float(v.x & 0xffff0000u); vf[2] = __uint_as_float(v.y << 16); vf[3] = __uint_as_float(v.y & 0xffff0000u);
;             vf[4] = __uint_as_float(v.z << 16); vf[5] = __uint_as_float(v.z & 0xffff0000u); vf[6] = __uint_as_float(v.w << 16); vf[7] = __uint_as_float(v.w & 0xffff0000u);
;             gf[0] = __uint_as_float(gt.x << 16); gf[1] = __uint_as_float(gt.x & 0xffff0000u); gf[2] = __uint_as_float(gt.y << 16); gf[3] = __uint_as_float(gt.y & 0xffff0000u);
;             gf[4] = __uint_as_float(gt.z << 16); gf[5] = __uint_as_float(gt.z & 0xffff0000u); gf[6] = __uint_as_float(gt.w << 16); gf[7] = __uint_as_float(gt.w & 0xffff0000u);
;             f32x4* d = (f32x4*)(hg + rr * 512 + c8 * 8);
;             d[0] = (f32x4){vf[0] * sigmoidf_(gf[0]), vf[1] * sigmoidf_(gf[1]), vf[2] * sigmoidf_(gf[2]), vf[3] * sigmoidf_(gf[3])};
;             d[1] = (f32x4){vf[4] * sigmoidf_(gf[4]), vf[5] * sigmoidf_(gf[5]), vf[6] * sigmoidf_(gf[6]), vf[7] * sigmoidf_(gf[7])};
;         }
.LBB0_576:
	s_or_b64 exec, exec, s[12:13]
	v_add_u32_e32 v0, 0xa00, v10
	v_ashrrev_i32_e32 v14, 6, v0
	v_cmp_gt_i32_e32 vcc, 46, v14
	s_and_saveexec_b64 s[12:13], vcc
	s_cbranch_execz .LBB0_580
	v_mov_b32_e32 v2, v184
	v_mov_b32_e32 v3, v185
	v_mov_b32_e32 v4, v186
	v_mov_b32_e32 v5, v187
	v_mov_b32_e32 v6, v188
	v_mov_b32_e32 v7, v189
	v_mov_b32_e32 v8, v190
	v_mov_b32_e32 v9, v191
	v_lshlrev_b32_e32 v0, 16, v6
	v_and_b32_e32 v12, 0xffff0000, v6
	v_mul_f32_e32 v0, 0xbfb8aa3b, v0
	v_exp_f32_e32 v6, v0
	v_mul_f32_e32 v0, 0xbfb8aa3b, v12
	v_lshlrev_b32_e32 v13, 16, v7
	v_and_b32_e32 v15, 0xffff0000, v7
	v_exp_f32_e32 v7, v0
	v_lshlrev_b32_e32 v16, 16, v8
	v_and_b32_e32 v17, 0xffff0000, v8
	v_lshlrev_b32_e32 v18, 16, v9
	v_pk_add_f32 v[6:7], v[6:7], 1.0 op_sel_hi:[1,0]
	v_and_b32_e32 v19, 0xffff0000, v9
	v_div_scale_f32 v0, s[2:3], v7, v7, 1.0
	v_lshlrev_b32_e32 v8, 16, v2
	v_and_b32_e32 v9, 0xffff0000, v2
	v_rcp_f32_e32 v2, v0
	v_lshl_add_u32 v11, v14, 11, v11
	v_fma_f32 v12, -v0, v2, 1.0
	v_fmac_f32_e32 v2, v12, v2
	v_div_scale_f32 v12, vcc, 1.0, v7, 1.0
	v_mul_f32_e32 v14, v12, v2
	v_fma_f32 v20, -v0, v14, v12
	v_fmac_f32_e32 v14, v20, v2
	v_fma_f32 v0, -v0, v14, v12
	v_div_fmas_f32 v0, v0, v2, v14
	v_div_fixup_f32 v7, v0, v7, 1.0
	v_div_scale_f32 v0, s[2:3], v6, v6, 1.0
	v_rcp_f32_e32 v2, v0
	s_nop 0
	v_fma_f32 v12, -v0, v2, 1.0
	v_fmac_f32_e32 v2, v12, v2
	v_div_scale_f32 v12, vcc, 1.0, v6, 1.0
	v_mul_f32_e32 v14, v12, v2
	v_fma_f32 v20, -v0, v14, v12
	v_fmac_f32_e32 v14, v20, v2
	v_fma_f32 v0, -v0, v14, v12
	v_div_fmas_f32 v0, v0, v2, v14
	v_div_fixup_f32 v6, v0, v6, 1.0
	v_mul_f32_e32 v0, 0xbfb8aa3b, v13
	v_pk_mul_f32 v[6:7], v[6:7], v[8:9]
	v_exp_f32_e32 v8, v0
	v_mul_f32_e32 v0, 0xbfb8aa3b, v15
	v_exp_f32_e32 v9, v0
	v_lshlrev_b32_e32 v2, 16, v3
	v_and_b32_e32 v3, 0xffff0000, v3
	v_pk_add_f32 v[8:9], v[8:9], 1.0 op_sel_hi:[1,0]
	s_nop 0
	v_div_scale_f32 v0, s[2:3], v9, v9, 1.0
	v_rcp_f32_e32 v12, v0
	s_nop 0
	v_fma_f32 v13, -v0, v12, 1.0
	v_fmac_f32_e32 v12, v13, v12
	v_div_scale_f32 v13, vcc, 1.0, v9, 1.0
	v_mul_f32_e32 v14, v13, v12
	v_fma_f32 v15, -v0, v14, v13
	v_fmac_f32_e32 v14, v15, v12
	v_fma_f32 v0, -v0, v14, v13
	v_div_fmas_f32 v0, v0, v12, v14
	v_div_fixup_f32 v9, v0, v9, 1.0
	v_div_scale_f32 v0, s[2:3], v8, v8, 1.0
	v_rcp_f32_e32 v12, v0
	s_nop 0
	v_fma_f32 v13, -v0, v12, 1.0
	v_fmac_f32_e32 v12, v13, v12
	v_div_scale_f32 v13, vcc, 1.0, v8, 1.0
	v_mul_f32_e32 v14, v13, v12
	v_fma_f32 v15, -v0, v14, v13
	v_fmac_f32_e32 v14, v15, v12
	v_fma_f32 v0, -v0, v14, v13
	v_div_fmas_f32 v0, v0, v12, v14
	v_div_fixup_f32 v8, v0, v8, 1.0
	v_mul_f32_e32 v0, 0xbfb8aa3b, v16
	v_pk_mul_f32 v[8:9], v[8:9], v[2:3]
	v_exp_f32_e32 v2, v0
	v_mul_f32_e32 v0, 0xbfb8aa3b, v17
	v_exp_f32_e32 v3, v0
	ds_write_b128 v11, v[6:9]
	v_lshlrev_b32_e32 v6, 16, v4
	v_and_b32_e32 v7, 0xffff0000, v4
	v_pk_add_f32 v[2:3], v[2:3], 1.0 op_sel_hi:[1,0]
	s_nop 0
	v_div_scale_f32 v0, s[2:3], v3, v3, 1.0
	v_rcp_f32_e32 v4, v0
	s_nop 0
	v_fma_f32 v8, -v0, v4, 1.0
	v_fmac_f32_e32 v4, v8, v4
	v_div_scale_f32 v8, vcc, 1.0, v3, 1.0
	v_mul_f32_e32 v9, v8, v4
	v_fma_f32 v12, -v0, v9, v8
	v_fmac_f32_e32 v9, v12, v4
	v_fma_f32 v0, -v0, v9, v8
	v_div_fmas_f32 v0, v0, v4, v9
	v_div_fixup_f32 v3, v0, v3, 1.0
	v_div_scale_f32 v0, s[2:3], v2, v2, 1.0
	v_rcp_f32_e32 v4, v0
	s_nop 0
	v_fma_f32 v8, -v0, v4, 1.0
	v_fmac_f32_e32 v4, v8, v4
	v_div_scale_f32 v8, vcc, 1.0, v2, 1.0
	v_mul_f32_e32 v9, v8, v4
	v_fma_f32 v12, -v0, v9, v8
	v_fmac_f32_e32 v9, v12, v4
	v_fma_f32 v0, -v0, v9, v8
	v_div_fmas_f32 v0, v0, v4, v9
	v_div_fixup_f32 v2, v0, v2, 1.0
	v_mul_f32_e32 v0, 0xbfb8aa3b, v18
	v_pk_mul_f32 v[2:3], v[2:3], v[6:7]
	v_exp_f32_e32 v6, v0
	v_mul_f32_e32 v0, 0xbfb8aa3b, v19
	v_exp_f32_e32 v7, v0
	v_lshlrev_b32_e32 v4, 16, v5
	v_and_b32_e32 v5, 0xffff0000, v5
	v_pk_add_f32 v[6:7], v[6:7], 1.0 op_sel_hi:[1,0]
	s_nop 0
	v_div_scale_f32 v0, s[2:3], v7, v7, 1.0
	v_rcp_f32_e32 v8, v0
	s_nop 0
	v_fma_f32 v9, -v0, v8, 1.0
	v_fmac_f32_e32 v8, v9, v8
	v_div_scale_f32 v9, vcc, 1.0, v7, 1.0
	v_mul_f32_e32 v12, v9, v8
	v_fma_f32 v13, -v0, v12, v9
	v_fmac_f32_e32 v12, v13, v8
	v_fma_f32 v0, -v0, v12, v9
	v_div_fmas_f32 v0, v0, v8, v12
	v_div_fixup_f32 v7, v0, v7, 1.0
	v_div_scale_f32 v0, s[2:3], v6, v6, 1.0
	v_rcp_f32_e32 v8, v0
	s_nop 0
	v_fma_f32 v9, -v0, v8, 1.0
	v_fmac_f32_e32 v8, v9, v8
	v_div_scale_f32 v9, vcc, 1.0, v6, 1.0
	v_mul_f32_e32 v12, v9, v8
	v_fma_f32 v13, -v0, v12, v9
	v_fmac_f32_e32 v12, v13, v8
	v_fma_f32 v0, -v0, v12, v9
	v_div_fmas_f32 v0, v0, v8, v12
	v_div_fixup_f32 v6, v0, v6, 1.0
	v_pk_mul_f32 v[4:5], v[6:7], v[4:5]
	ds_write_b128 v11, v[2:5] offset:16

; __device__ __forceinline__ void pool_item(PP p, unsigned char* shm, int item) {
;     ...
;     const int row0 = item * 32, b = row0 / SEQ, l0 = row0 % SEQ;
; #pragma unroll
;     for (int i = 0; i < 6; ++i) {
;         const int ci = tid + i * 512, rr = ci >> 6, c8 = ci & 63, ll = l0 - 16 + rr;
;         u32x4 v = (u32x4){0u, 0u, 0u, 0u};
;         if (ll >= 0) v = *(const u32x4*)(proj + PJ_UB + (size_t)(b * SEQ + ll) * 512 + c8 * 8);
;         f32x4* d = (f32x4*)(ut + rr * 512 + c8 * 8);
;         d[0] = (f32x4){__uint_as_float(v.x << 16), __uint_as_float(v.x & 0xffff0000u), __uint_as_float(v.y << 16), __uint_as_float(v.y & 0xffff0000u)};
;         d[1] = (f32x4){__uint_as_float(v.z << 16), __uint_as_float(v.z & 0xffff0000u), __uint_as_float(v.w << 16), __uint_as_float(v.w & 0xffff0000u)};
;     }
.LBB0_581:
	s_and_b64 vcc, exec, s[2:3]
	s_cbranch_vccz .LBB0_624
	v_mov_b32_e32 v8, v222
	s_lshl_b32 s2, s14, 5
	s_and_b32 s12, s2, 0x7e0
	v_and_b32_e32 v3, 63, v8
	s_add_i32 s12, s12, -16
	v_lshlrev_b32_e32 v0, 4, v3
	v_ashrrev_i32_e32 v12, 6, v8
	s_and_b32 s9, s2, 0x1800
	s_waitcnt lgkmcnt(0)
	v_lshl_add_u64 v[4:5], s[34:35], 0, v[0:1]
	s_mov_b64 s[2:3], 0x1e600000
	v_add_u32_e32 v0, s12, v12
	v_lshl_add_u64 v[10:11], v[4:5], 0, s[2:3]
	v_mov_b32_e32 v130, v8
	v_ashrrev_i32_e32 v130, 6, v130
	v_add_u32_e32 v132, s12, v130
	v_mov_b32_e32 v133, 0
	v_mov_b32_e32 v136, 0
	v_mov_b32_e32 v137, 0
	v_mov_b32_e32 v138, 0
	v_mov_b32_e32 v139, 0
	v_cmp_lt_i32_e32 vcc, -1, v132
	s_and_saveexec_b64 s[2:3], vcc
	s_cbranch_execz .Lpool_skip_0
	v_add_u32_e32 v132, s9, v132
	v_lshlrev_b64 v[134:135], 10, v[132:133]
	v_lshl_add_u64 v[134:135], v[10:11], 0, v[134:135]
	global_load_dwordx4 v[136:139], v[134:135], off
.Lpool_skip_0:
	s_or_b64 exec, exec, s[2:3]
	v_add_u32_e32 v130, 0x200, v8
	v_ashrrev_i32_e32 v130, 6, v130
	v_add_u32_e32 v132, s12, v130
	v_mov_b32_e32 v133, 0
	v_mov_b32_e32 v140, 0
	v_mov_b32_e32 v141, 0
	v_mov_b32_e32 v142, 0
	v_mov_b32_e32 v143, 0
	v_cmp_lt_i32_e32 vcc, -1, v132
	s_and_saveexec_b64 s[2:3], vcc
	s_cbranch_execz .Lpool_skip_1
	v_add_u32_e32 v132, s9, v132
	v_lshlrev_b64 v[134:135], 10, v[132:133]
	v_lshl_add_u64 v[134:135], v[10:11], 0, v[134:135]
	global_load_dwordx4 v[140:143], v[134:135], off
.Lpool_skip_1:
	s_or_b64 exec, exec, s[2:3]
	v_add_u32_e32 v130, 0x400, v8
	v_ashrrev_i32_e32 v130, 6, v130
	v_add_u32_e32 v132, s12, v130
	v_mov_b32_e32 v133, 0
	v_mov_b32_e32 v144, 0
	v_mov_b32_e32 v145, 0
	v_mov_b32_e32 v146, 0
	v_mov_b32_e32 v147, 0
	v_cmp_lt_i32_e32 vcc, -1, v132
	s_and_saveexec_b64 s[2:3], vcc
	s_cbranch_execz .Lpool_skip_2
	v_add_u32_e32 v132, s9, v132
	v_lshlrev_b64 v[134:135], 10, v[132:133]
	v_lshl_add_u64 v[134:135], v[10:11], 0, v[134:135]
	global_load_dwordx4 v[144:147], v[134:135], off
.Lpool_skip_2:
	s_or_b64 exec, exec, s[2:3]
	v_add_u32_e32 v130, 0x600, v8
	v_ashrrev_i32_e32 v130, 6, v130
	v_add_u32_e32 v132, s12, v130
	v_mov_b32_e32 v133, 0
	v_mov_b32_e32 v148, 0
	v_mov_b32_e32 v149, 0
	v_mov_b32_e32 v150, 0
	v_mov_b32_e32 v151, 0
	v_cmp_lt_i32_e32 vcc, -1, v132
	s_and_saveexec_b64 s[2:3], vcc
	s_cbranch_execz .Lpool_skip_3
	v_add_u32_e32 v132, s9, v132
	v_lshlrev_b64 v[134:135], 10, v[132:133]
	v_lshl_add_u64 v[134:135], v[10:11], 0, v[134:135]
	global_load_dwordx4 v[148:151], v[134:135], off
.Lpool_skip_3:
	s_or_b64 exec, exec, s[2:3]
	v_add_u32_e32 v130, 0x800, v8
	v_ashrrev_i32_e32 v130, 6, v130
	v_add_u32_e32 v132, s12, v130
	v_mov_b32_e32 v133, 0
	v_mov_b32_e32 v152, 0
	v_mov_b32_e32 v153, 0
	v_mov_b32_e32 v154, 0
	v_mov_b32_e32 v155, 0
	v_cmp_lt_i32_e32 vcc, -1, v132
	s_and_saveexec_b64 s[2:3], vcc
	s_cbranch_execz .Lpool_skip_4
	v_add_u32_e32 v132, s9, v132
	v_lshlrev_b64 v[134:135], 10, v[132:133]
	v_lshl_add_u64 v[134:135], v[10:11], 0, v[134:135]
	global_load_dwordx4 v[152:155], v[134:135], off
.Lpool_skip_4:
	s_or_b64 exec, exec, s[2:3]
	v_add_u32_e32 v130, 0xa00, v8
	v_ashrrev_i32_e32 v130, 6, v130
	v_add_u32_e32 v132, s12, v130
	v_mov_b32_e32 v133, 0
	v_mov_b32_e32 v156, 0
	v_mov_b32_e32 v157, 0
	v_mov_b32_e32 v158, 0
	v_mov_b32_e32 v159, 0
	v_cmp_lt_i32_e32 vcc, -1, v132
	s_and_saveexec_b64 s[2:3], vcc
	s_cbranch_execz .Lpool_skip_5
	v_add_u32_e32 v132, s9, v132
	v_lshlrev_b64 v[134:135], 10, v[132:133]
	v_lshl_add_u64 v[134:135], v[10:11], 0, v[134:135]
	global_load_dwordx4 v[156:159], v[134:135], off
; __device__ __forceinline__ void pool_item(PP p, unsigned char* shm, int item) {
;     ...
;     for (int i = 0; i < 6; ++i) {
;         const int ci = tid + i * 512, rr = ci >> 6, c8 = ci & 63, ll = l0 - 16 + rr;
;         u32x4 v = (u32x4){0u, 0u, 0u, 0u};
;         if (ll >= 0) v = *(const u32x4*)(proj + PJ_UB + (size_t)(b * SEQ + ll) * 512 + c8 * 8);
;         f32x4* d = (f32x4*)(ut + rr * 512 + c8 * 8);
;         d[0] = (f32x4){__uint_as_float(v.x << 16), __uint_as_float(v.x & 0xffff0000u), __uint_as_float(v.y << 16), __uint_as_float(v.y & 0xffff0000u)};
;         d[1] = (f32x4){__uint_as_float(v.z << 16), __uint_as_float(v.z & 0xffff0000u), __uint_as_float(v.w << 16), __uint_as_float(v.w & 0xffff0000u)};
;     }
;     __syncthreads();
.Lpool_skip_5:
	s_or_b64 exec, exec, s[2:3]
	s_waitcnt vmcnt(0)
	v_mov_b32_e32 v2, 0
	v_mov_b32_e32 v4, v136
	v_mov_b32_e32 v5, v137
	v_mov_b32_e32 v6, v138
	v_mov_b32_e32 v7, v139
	v_lshl_add_u32 v9, v3, 5, 0
	v_lshl_add_u32 v0, v12, 11, v9
	s_waitcnt vmcnt(0)
	v_lshlrev_b32_e32 v12, 16, v4
	v_and_b32_e32 v13, 0xffff0000, v4
	v_lshlrev_b32_e32 v14, 16, v5
	v_and_b32_e32 v15, 0xffff0000, v5
	v_lshlrev_b32_e32 v4, 16, v6
	v_and_b32_e32 v5, 0xffff0000, v6
	v_lshlrev_b32_e32 v6, 16, v7
	v_and_b32_e32 v7, 0xffff0000, v7
	ds_write_b128 v0, v[12:15]
	ds_write_b128 v0, v[4:7] offset:16
	v_add_u32_e32 v0, 0x200, v8
	v_ashrrev_i32_e32 v6, 6, v0
	v_add_u32_e32 v0, s12, v6
	v_mov_b32_e32 v2, v140
	v_mov_b32_e32 v3, v141
	v_mov_b32_e32 v4, v142
	v_mov_b32_e32 v5, v143
	v_lshl_add_u32 v0, v6, 11, v9
	v_lshlrev_b32_e32 v12, 16, v2
	v_and_b32_e32 v13, 0xffff0000, v2
	v_lshlrev_b32_e32 v14, 16, v3
	v_and_b32_e32 v15, 0xffff0000, v3
	v_lshlrev_b32_e32 v2, 16, v4
	v_and_b32_e32 v3, 0xffff0000, v4
	v_lshlrev_b32_e32 v4, 16, v5
	v_and_b32_e32 v5, 0xffff0000, v5
	ds_write_b128 v0, v[12:15]
	ds_write_b128 v0, v[2:5] offset:16
	v_add_u32_e32 v0, 0x400, v8
	v_ashrrev_i32_e32 v3, 6, v0
	v_add_u32_e32 v0, s12, v3
	v_mov_b32_e32 v2, 0
	v_mov_b32_e32 v4, v144
	v_mov_b32_e32 v5, v145
	v_mov_b32_e32 v6, v146
	v_mov_b32_e32 v7, v147
	v_lshl_add_u32 v0, v3, 11, v9
	v_lshlrev_b32_e32 v12, 16, v4
	v_and_b32_e32 v13, 0xffff0000, v4
	v_lshlrev_b32_e32 v14, 16, v5
	v_and_b32_e32 v15, 0xffff0000, v5
	v_lshlrev_b32_e32 v4, 16, v6
	v_and_b32_e32 v5, 0xffff0000, v6
	v_lshlrev_b32_e32 v6, 16, v7
	v_and_b32_e32 v7, 0xffff0000, v7
	ds_write_b128 v0, v[12:15]
	ds_write_b128 v0, v[4:7] offset:16
	v_add_u32_e32 v0, 0x600, v8
	v_ashrrev_i32_e32 v6, 6, v0
	v_add_u32_e32 v0, s12, v6
	v_mov_b32_e32 v2, v148
	v_mov_b32_e32 v3, v149
	v_mov_b32_e32 v4, v150
	v_mov_b32_e32 v5, v151
	v_lshl_add_u32 v0, v6, 11, v9
	v_lshlrev_b32_e32 v12, 16, v2
	v_and_b32_e32 v13, 0xffff0000, v2
	v_lshlrev_b32_e32 v14, 16, v3
	v_and_b32_e32 v15, 0xffff0000, v3
	v_lshlrev_b32_e32 v2, 16, v4
	v_and_b32_e32 v3, 0xffff0000, v4
	v_lshlrev_b32_e32 v4, 16, v5
	v_and_b32_e32 v5, 0xffff0000, v5
	ds_write_b128 v0, v[12:15]
	ds_write_b128 v0, v[2:5] offset:16
	v_add_u32_e32 v0, 0x800, v8
	v_ashrrev_i32_e32 v3, 6, v0
	v_add_u32_e32 v0, s12, v3
	v_mov_b32_e32 v2, 0
	v_mov_b32_e32 v4, v152
	v_mov_b32_e32 v5, v153
	v_mov_b32_e32 v6, v154
	v_mov_b32_e32 v7, v155
	v_lshl_add_u32 v0, v3, 11, v9
	v_lshlrev_b32_e32 v12, 16, v4
	v_and_b32_e32 v13, 0xffff0000, v4
	v_lshlrev_b32_e32 v14, 16, v5
	v_and_b32_e32 v15, 0xffff0000, v5
	v_lshlrev_b32_e32 v4, 16, v6
	v_and_b32_e32 v5, 0xffff0000, v6
	v_lshlrev_b32_e32 v6, 16, v7
	v_and_b32_e32 v7, 0xffff0000, v7
	ds_write_b128 v0, v[12:15]
	ds_write_b128 v0, v[4:7] offset:16
	v_add_u32_e32 v0, 0xa00, v8
	v_ashrrev_i32_e32 v6, 6, v0
	v_add_u32_e32 v0, s12, v6
	v_mov_b32_e32 v2, v156
	v_mov_b32_e32 v3, v157
	v_mov_b32_e32 v4, v158
	v_mov_b32_e32 v5, v159
	v_ashrrev_i32_e32 v0, 7, v8
	v_lshl_add_u32 v6, v6, 11, v9
	v_lshlrev_b32_e32 v10, 16, v2
	v_and_b32_e32 v11, 0xffff0000, v2
	v_lshlrev_b32_e32 v12, 16, v3
	v_and_b32_e32 v13, 0xffff0000, v3
	v_lshlrev_b32_e32 v2, 16, v4
	v_and_b32_e32 v3, 0xffff0000, v4
	v_lshlrev_b32_e32 v4, 16, v5
	v_and_b32_e32 v5, 0xffff0000, v5
	v_lshlrev_b32_e64 v0, v0, 2
	ds_write_b128 v6, v[2:5] offset:16
	v_cmp_lt_i32_e32 vcc, 0, v0
	v_lshlrev_b32_e32 v4, 2, v8
	ds_write_b128 v6, v[10:13]
	s_waitcnt lgkmcnt(0)
	s_barrier
	s_and_saveexec_b64 s[2:3], vcc
	s_xor_b64 s[2:3], exec, s[2:3]
	s_cbranch_execz .LBB0_598
	v_lshlrev_b32_e32 v4, 2, v8
	v_readlane_b32 s9, v254, 62
	v_mov_b32_e32 v6, 0
	s_mov_b64 s[12:13], 0
	v_add_u32_e32 v2, s9, v4
	v_mov_b32_e32 v3, v0
